# NSA select/window attention work queue: next item claimed at the start of the current item (atomic overlapped), published from a register at the loop top
# baseline (speedup 1.0000x reference)
; __global__ void __launch_bounds__(512, 2) mega_fwd(Args a) {
;     ...
;             for (;;) {
;                 __syncthreads();
;                 if (threadIdx.x == 0) qslot[0] = atomicAdd(qctr, 1u);
.Ldeq_first:
	s_mov_b64 s[0:1], exec
	v_readlane_b32 s6, v252, 2
	v_readlane_b32 s7, v252, 3
	s_nop 0
	s_and_b64 exec, s[0:1], s[6:7]
	s_cbranch_execz .Ldeq_skip0
	v_readlane_b32 s6, v255, 45
	v_readlane_b32 s7, v255, 46
	v_mov_b32_e32 v244, 1
	s_nop 4
	global_atomic_add v244, v0, v244, s[6:7] sc0
.Ldeq_skip0:
	s_mov_b64 exec, s[0:1]
	s_waitcnt vmcnt(0)
	s_branch .LBB0_49

; template <int MODE>
; __device__ __forceinline__ void attn_pass(LAS unsigned char* lds, const bf16_t* base, int gk, int q0, const float* relb_b, const unsigned* selrow, f32x4 (&o)[2][4]) {
;     ...
;         for (int ks = 0; ks < 2; ++ks) qf[qt][ks] = *(const bf16x8*)(qp + (size_t)(qw0 + qt * 16 + c) * QP + ks * 32 + g * 8);
;     const int kb_hi = q0 >> 6;
;     unsigned todo;
;     unsigned sel[2] = {0xffffffffu, 0xffffffffu};
;     unsigned selw = 0xffffffffu;
;     if (MODE == MODE_BSLC) {
;         sel[0] = selrow[qw0 + c]; sel[1] = selrow[qw0 + 16 + c];
;         unsigned u = sel[0] | sel[1];
; #pragma unroll
;         for (int off = 1; off < 64; off <<= 1) u |= __shfl_xor(u, off);
;         selw = __builtin_amdgcn_readfirstlane(u);
;         unsigned v = selrow[q0 + lane];
; #pragma unroll
;         for (int off = 1; off < 64; off <<= 1) v |= __shfl_xor(v, off);
;         todo = __builtin_amdgcn_readfirstlane(v) & (0xffffffffu >> (31 - kb_hi));
;     } else {
;         const int kb_lo = kb_hi >= 8 ? kb_hi - 8 : 0;
;         todo = (0xffffffffu >> (31 - kb_hi)) & (0xffffffffu << kb_lo);
;     }
;     __syncthreads();
;     if (tid < 512) { const int e = tid; lutw[e] = relb_b[(int)T5B[e & 127] * 16 + gk * 4 + (e >> 7)] * LOG2E; }
; __global__ void __launch_bounds__(512, 2) mega_fwd(Args a) {
;     ...
;             for (;;) {
;                 __syncthreads();
;                 if (threadIdx.x == 0) qslot[0] = atomicAdd(qctr, 1u);
;                 __syncthreads();
;                 const int it = (int)qslot[0];
;                 if (it >= 2048) break;
;                 item_attn_b(lds, BIG, Yb, Ycmp, relb, selm, it);
.LBB0_49:
	s_barrier
	s_mov_b64 s[0:1], exec
	v_readlane_b32 s4, v252, 2
	v_readlane_b32 s5, v252, 3
	s_and_b64 s[4:5], s[0:1], s[4:5]
	s_mov_b64 exec, s[4:5]
	s_cbranch_execz .LBB0_53
	s_waitcnt vmcnt(4)
	v_readlane_b32 s4, v254, 48
	s_nop 1
	v_mov_b32_e32 v2, s4
	ds_write_b32 v2, v244
.LBB0_53:
	s_or_b64 exec, exec, s[0:1]
	v_readlane_b32 s0, v254, 48
	s_waitcnt lgkmcnt(0)
	s_barrier
	v_mov_b32_e32 v1, s0
	ds_read_b32 v1, v1
	s_movk_i32 s0, 0x7ff
	s_waitcnt lgkmcnt(0)
	v_cmp_lt_i32_e32 vcc, s0, v1
	v_readfirstlane_b32 s5, v1
	s_mov_b64 s[0:1], -1
	s_cbranch_vccnz .LBB0_48
	s_mov_b64 s[0:1], exec
	v_readlane_b32 s6, v252, 2
	v_readlane_b32 s7, v252, 3
	s_nop 0
	s_and_b64 exec, s[0:1], s[6:7]
	s_cbranch_execz .Ldeq_skip
	v_readlane_b32 s6, v255, 45
	v_readlane_b32 s7, v255, 46
	v_mov_b32_e32 v244, 1
	s_nop 4
	global_atomic_add v244, v0, v244, s[6:7] sc0
.Ldeq_skip:
	s_mov_b64 exec, s[0:1]
	s_and_b32 s0, s5, 0xffffffc0
	s_bfe_u32 s19, s5, 0x50001
	s_and_b32 s4, s5, 1
	s_sub_i32 s36, 0x7c0, s0
	s_mul_i32 s0, s19, 0xe18000
	v_readlane_b32 s6, v252, 52
	v_readlane_b32 s7, v252, 53
	s_add_u32 s13, s6, s0
	s_addc_u32 s41, s7, 0
	s_lshl_b32 s40, s4, 2
	s_lshl_b32 s0, s19, 14
	v_readlane_b32 s1, v252, 14
	s_add_u32 s0, s1, s0
	v_readlane_b32 s1, v252, 15
	v_mov_b32_e32 v180, v214
	s_addc_u32 s1, s1, 0
	s_lshl_b32 s5, s4, 13
	v_mov_b32_e32 v10, v214
	s_add_u32 s0, s0, s5
	s_addc_u32 s1, s1, 0
	v_readfirstlane_b32 s5, v10
	s_bfe_u32 s7, s5, 0x20006
	s_or_b32 s8, s7, s40
	s_lshl_b32 s6, s8, 7
	s_add_u32 s10, s13, s6
	s_addc_u32 s11, s41, 0
	s_ashr_i32 s5, s5, 3
	s_and_b32 s6, s5, 0xffffffe0
	v_and_b32_e32 v1, 15, v10
	s_add_i32 s6, s6, s36
	v_or_b32_e32 v2, s6, v1
	v_ashrrev_i32_e32 v3, 31, v2
	v_lshl_add_u64 v[8:9], v[2:3], 2, s[0:1]
	v_and_or_b32 v12, v10, 63, s36
	v_mov_b32_e32 v13, v0
	v_lshl_add_u64 v[12:13], v[12:13], 2, s[0:1]
	global_load_dword v146, v[8:9], off
	global_load_dword v147, v[8:9], off offset:64
	global_load_dword v3, v[12:13], off
	v_mov_b32_e32 v9, v0
	v_and_b32_e32 v8, 48, v10
	v_lshl_add_u64 v[12:13], s[10:11], 0, v[8:9]
	v_or_b32_e32 v9, 16, v2
	v_mad_i64_i32 v[14:15], s[0:1], v2, s85, v[12:13]
	v_mad_i64_i32 v[12:13], s[0:1], v9, s85, v[12:13]
	global_load_dwordx4 v[40:43], v[14:15], off offset:1536
	global_load_dwordx4 v[44:47], v[14:15], off offset:1600
	global_load_dwordx4 v[48:51], v[12:13], off offset:1536
	global_load_dwordx4 v[52:55], v[12:13], off offset:1600
	v_cmp_lt_i32_e32 vcc, v219, v218
	s_barrier
	s_nop 0
	v_cndmask_b32_e32 v9, v217, v219, vcc
	v_lshlrev_b32_e32 v9, 2, v9
	v_cmp_lt_i32_e32 vcc, v220, v218
	s_waitcnt vmcnt(5)
	v_or_b32_e32 v11, v147, v146
	s_waitcnt vmcnt(4)
	ds_bpermute_b32 v12, v9, v3
	ds_bpermute_b32 v9, v9, v11
	v_cndmask_b32_e32 v13, v217, v220, vcc
	v_lshlrev_b32_e32 v13, 2, v13
	v_cmp_lt_i32_e32 vcc, v221, v218
	s_waitcnt lgkmcnt(1)
	v_or_b32_e32 v3, v12, v3
	s_waitcnt lgkmcnt(0)
	v_or_b32_e32 v9, v9, v11
	ds_bpermute_b32 v11, v13, v3
	ds_bpermute_b32 v12, v13, v9
	v_cndmask_b32_e32 v13, v217, v221, vcc
	v_lshlrev_b32_e32 v13, 2, v13
	v_cmp_lt_i32_e32 vcc, v222, v218
	s_waitcnt lgkmcnt(1)
	v_or_b32_e32 v3, v11, v3
	s_waitcnt lgkmcnt(0)
	v_or_b32_e32 v9, v12, v9
	ds_bpermute_b32 v11, v13, v3
	ds_bpermute_b32 v12, v13, v9
	v_cndmask_b32_e32 v13, v217, v222, vcc
	v_lshlrev_b32_e32 v13, 2, v13
	v_cmp_lt_i32_e32 vcc, v223, v218
	s_waitcnt lgkmcnt(1)
	v_or_b32_e32 v3, v11, v3
	s_waitcnt lgkmcnt(0)
	v_or_b32_e32 v9, v12, v9
	ds_bpermute_b32 v11, v13, v3
	ds_bpermute_b32 v12, v13, v9
	v_cndmask_b32_e32 v13, v217, v223, vcc
	v_lshlrev_b32_e32 v178, 2, v13
	v_cmp_lt_i32_e32 vcc, v224, v218
	s_waitcnt lgkmcnt(1)
	v_or_b32_e32 v3, v11, v3
	s_waitcnt lgkmcnt(0)
	v_or_b32_e32 v9, v12, v9
	ds_bpermute_b32 v11, v178, v3
	ds_bpermute_b32 v12, v178, v9
	v_cndmask_b32_e32 v13, v217, v224, vcc
	v_lshlrev_b32_e32 v179, 2, v13
	v_cmp_gt_i32_e32 vcc, s33, v10
	s_waitcnt lgkmcnt(1)
	v_or_b32_e32 v3, v11, v3
	s_waitcnt lgkmcnt(0)
	v_or_b32_e32 v9, v12, v9
	ds_bpermute_b32 v11, v179, v3
	ds_bpermute_b32 v12, v179, v9
	s_waitcnt lgkmcnt(1)
	v_or_b32_e32 v3, v11, v3
	s_waitcnt lgkmcnt(0)
	v_or_b32_e32 v9, v12, v9
	v_readfirstlane_b32 s9, v3
	v_readfirstlane_b32 s44, v9
	s_and_saveexec_b64 s[0:1], vcc
	s_cbranch_execz .LBB0_56
	v_and_b32_e32 v3, 0x7f, v10
	s_getpc_b64 s[10:11]
	s_add_u32 s10, s10, T5B@rel32@lo+4
	s_addc_u32 s11, s11, T5B@rel32@hi+12
	global_load_ubyte v3, v3, s[10:11]
	v_ashrrev_i32_e32 v9, 7, v10
	v_readlane_b32 s48, v255, 4
	v_readlane_b32 s52, v255, 8
	v_readlane_b32 s53, v255, 9
	v_readlane_b32 s49, v255, 5
	v_readlane_b32 s50, v255, 6
	v_readlane_b32 s51, v255, 7
	v_readlane_b32 s54, v255, 10
	v_readlane_b32 s55, v255, 11
	v_readlane_b32 s56, v255, 12
	v_readlane_b32 s57, v255, 13
	v_readlane_b32 s58, v255, 14
	v_readlane_b32 s59, v255, 15
	v_readlane_b32 s60, v255, 16
	v_readlane_b32 s61, v255, 17
	v_readlane_b32 s62, v255, 18
	v_readlane_b32 s63, v255, 19
	s_nop 1
	v_add_u32_e32 v228, 0x1f0, v9
	v_add_u32_e32 v228, s40, v228
	v_ashrrev_i32_e32 v229, 31, v228
	v_lshl_add_u64 v[228:229], v[228:229], 2, s[52:53]
	global_load_dword v230, v[228:229], off offset:32
	s_waitcnt vmcnt(0)
	v_lshlrev_b32_e32 v3, 4, v3
	v_add3_u32 v12, v9, s40, v3
	v_ashrrev_i32_e32 v13, 31, v12
	v_lshl_add_u64 v[12:13], v[12:13], 2, s[52:53]
	global_load_dword v3, v[12:13], off offset:32
	v_lshl_add_u32 v9, v10, 2, 0
	s_waitcnt vmcnt(0)
	v_mul_f32_e32 v3, 0x3fb8aa3b, v3
	ds_write_b32 v9, v3 offset:36864
	v_mul_f32_e32 v230, 0x3fb8aa3b, v230
	v_ashrrev_i32_e32 v231, 7, v10
	v_mul_u32_u24_e32 v231, 0xa00, v231
	v_and_b32_e32 v232, 0x7f, v10
	v_lshl_add_u32 v233, v232, 2, v231
	v_and_b32_e32 v234, 64, v10
	v_lshl_add_u32 v234, v234, 5, v233
	v_mov_b32_e32 v235, 0xf149f2ca
	ds_write_b32 v233, v3 offset:41216
	ds_write_b32 v234, v235 offset:40960
	ds_write_b32 v233, v230 offset:41728
	ds_write_b32 v233, v230 offset:42240
	ds_write_b32 v233, v230 offset:42752
